# grid barrier leader: bump the XCD generation before its own L1 invalidate (followers released earlier)
# speedup vs baseline: 1.0147x; 1.0051x over previous
.LBB0_133:
	s_or_b64 exec, exec, s[8:9]
	v_mov_b32_e32 v1, 0x2000
	v_mov_b32_e32 v2, 1
	s_waitcnt vmcnt(0)
	global_atomic_add v1, v2, s[6:7] offset:1024
	buffer_inv sc1
	s_waitcnt vmcnt(0)

.LBB0_639:
	s_or_b64 exec, exec, s[6:7]
	v_mov_b32_e32 v2, 0x2000
	v_mov_b32_e32 v3, 1
	s_waitcnt vmcnt(0)
	global_atomic_add v2, v3, s[4:5] offset:1024
	buffer_inv sc1
	s_waitcnt vmcnt(0)

.LBB0_816:
	s_or_b64 exec, exec, s[8:9]
	v_mov_b32_e32 v2, 0x2000
	v_mov_b32_e32 v3, 1
	s_waitcnt vmcnt(0)
	global_atomic_add v2, v3, s[6:7] offset:1024
	buffer_inv sc1
	s_waitcnt vmcnt(0)

.LBB0_1142:
	s_or_b64 exec, exec, s[6:7]
	v_mov_b32_e32 v1, 0x2000
	v_mov_b32_e32 v2, 1
	s_waitcnt vmcnt(0)
	global_atomic_add v1, v2, s[4:5] offset:1024
	buffer_inv sc1
	s_waitcnt vmcnt(0)
